# adds: attention unit epilogue output stores widened 16x dwordx2 -> 8x dwordx4 via v_permlane32_swap half-wave exchange
# speedup vs baseline: 1.0044x; 1.0044x over previous
; __device__ __forceinline__ int crow(int r, int hi) { return (r & 3) + 8 * (r >> 2) + 4 * hi; }
; __device__ __forceinline__ void attn_unit(const bf16* Hb, const bf16* KD, const bf16* VD, bf16* MIX, int row0, int S, int head, int qb, float lam, const float* dng, float kn0, float kn1, LAS unsigned char* lds, int wave_u) {
;     ...
;     __syncthreads();
;     if (c == 0) {
;         float ss = 0.f;
; #pragma unroll
;         for (int b = 0; b < 4; ++b)
; #pragma unroll
;             for (int r = 0; r < 16; ++r) { const float v = o[b][r] * rl - X[(qs * 32 + r32e) * XS + 32 * b + crow(r, hhe)]; o[b][r] = v; ss += v * v; }
;         ss += __shfl_xor(ss, 32);
.LBB0_679:
	s_andn2_b64 vcc, exec, s[34:35]
	s_waitcnt lgkmcnt(0)
	s_barrier
	s_cbranch_vccnz .LBB0_607
	v_or_b32_e32 v68, s70, v79
	s_movk_i32 s0, 0x210
	v_mul_lo_u32 v68, v68, s0
	v_add3_u32 v80, 0, v68, v66
	ds_read_b128 v[68:71], v80
	ds_read_b128 v[72:75], v80 offset:32
	ds_read_b128 v[82:85], v80 offset:288
	s_lshl_b32 s2, s69, 7
	s_lshl_b32 s4, s2, 1
	s_waitcnt lgkmcnt(2)
	v_fma_f32 v68, v50, v0, -v68
	v_fma_f32 v50, v51, v0, -v69
	v_fma_f32 v51, v52, v0, -v70
	v_fma_f32 v53, v53, v0, -v71
	s_waitcnt lgkmcnt(1)
	v_fma_f32 v69, v54, v0, -v72
	v_fma_f32 v55, v55, v0, -v73
	ds_read_b128 v[70:73], v80 offset:64
	v_mul_f32_e32 v81, v50, v50
	v_fmac_f32_e32 v81, v68, v68
	v_fma_f32 v56, v56, v0, -v74
	v_fma_f32 v57, v57, v0, -v75
	s_waitcnt lgkmcnt(0)
	v_fma_f32 v54, v60, v0, -v72
	v_fma_f32 v52, v61, v0, -v73
	ds_read_b128 v[72:75], v80 offset:96
	v_fmac_f32_e32 v81, v51, v51
	v_fmac_f32_e32 v81, v53, v53
	v_fmac_f32_e32 v81, v69, v69
	v_fmac_f32_e32 v81, v55, v55
	v_fmac_f32_e32 v81, v56, v56
	v_fma_f32 v70, v58, v0, -v70
	v_fma_f32 v58, v59, v0, -v71
	s_waitcnt lgkmcnt(0)
	v_fma_f32 v71, v62, v0, -v72
	v_fma_f32 v63, v63, v0, -v73
	v_fma_f32 v62, v64, v0, -v74
	v_fma_f32 v61, v65, v0, -v75
	ds_read_b128 v[72:75], v80 offset:128
	v_fmac_f32_e32 v81, v57, v57
	v_fmac_f32_e32 v81, v70, v70
	v_fmac_f32_e32 v81, v58, v58
	v_fmac_f32_e32 v81, v54, v54
	v_fmac_f32_e32 v81, v52, v52
	s_waitcnt lgkmcnt(0)
	v_fma_f32 v60, v34, v0, -v72
	v_fma_f32 v59, v35, v0, -v73
	v_fma_f32 v35, v36, v0, -v74
	v_fma_f32 v34, v37, v0, -v75
	ds_read_b128 v[72:75], v80 offset:160
	v_fmac_f32_e32 v81, v71, v71
	v_fmac_f32_e32 v81, v63, v63
	v_fmac_f32_e32 v81, v62, v62
	v_fmac_f32_e32 v81, v61, v61
	v_fmac_f32_e32 v81, v60, v60
	s_waitcnt lgkmcnt(0)
	v_fma_f32 v64, v40, v0, -v74
	v_fma_f32 v41, v41, v0, -v75
	ds_read_b128 v[74:77], v80 offset:192
	v_fmac_f32_e32 v81, v59, v59
	v_fmac_f32_e32 v81, v35, v35
	v_fmac_f32_e32 v81, v34, v34
	v_fma_f32 v72, v38, v0, -v72
	v_fmac_f32_e32 v81, v72, v72
	v_fma_f32 v65, v39, v0, -v73
	v_fmac_f32_e32 v81, v65, v65
	s_waitcnt lgkmcnt(0)
	v_fma_f32 v39, v42, v0, -v74
	v_fma_f32 v38, v43, v0, -v75
	v_fma_f32 v37, v44, v0, -v76
	v_fma_f32 v36, v45, v0, -v77
	ds_read_b128 v[74:77], v80 offset:224
	v_fmac_f32_e32 v81, v64, v64
	v_fmac_f32_e32 v81, v41, v41
	v_fmac_f32_e32 v81, v39, v39
	v_fmac_f32_e32 v81, v38, v38
	v_fmac_f32_e32 v81, v37, v37
	s_waitcnt lgkmcnt(0)
	v_fma_f32 v73, v46, v0, -v74
	v_fma_f32 v47, v47, v0, -v75
	v_fma_f32 v45, v48, v0, -v76
	v_fma_f32 v44, v49, v0, -v77
	ds_read_b128 v[74:77], v80 offset:256
	v_fmac_f32_e32 v81, v36, v36
	v_fmac_f32_e32 v81, v73, v73
	v_fmac_f32_e32 v81, v47, v47
	v_fmac_f32_e32 v81, v45, v45
	v_fmac_f32_e32 v81, v44, v44
	s_waitcnt lgkmcnt(0)
	v_fma_f32 v43, v18, v0, -v74
	v_fmac_f32_e32 v81, v43, v43
	v_fma_f32 v42, v19, v0, -v75
	v_fmac_f32_e32 v81, v42, v42
	v_fma_f32 v40, v20, v0, -v76
	v_fma_f32 v75, v22, v0, -v82
	v_fma_f32 v74, v23, v0, -v83
	v_fma_f32 v49, v24, v0, -v84
	v_fma_f32 v48, v25, v0, -v85
	ds_read_b128 v[82:85], v80 offset:352
	v_fmac_f32_e32 v81, v40, v40
	v_fma_f32 v20, v21, v0, -v77
	ds_read_b128 v[22:25], v80 offset:320
	v_fmac_f32_e32 v81, v20, v20
	v_fmac_f32_e32 v81, v75, v75
	v_fmac_f32_e32 v81, v74, v74
	v_fmac_f32_e32 v81, v49, v49
	s_waitcnt lgkmcnt(1)
	v_fma_f32 v78, v30, v0, -v82
	v_fma_f32 v77, v31, v0, -v83
	v_fma_f32 v76, v32, v0, -v84
	v_fma_f32 v33, v33, v0, -v85
	ds_read_b128 v[82:85], v80 offset:384
	v_fmac_f32_e32 v81, v48, v48
	s_waitcnt lgkmcnt(1)
	v_fma_f32 v46, v26, v0, -v22
	v_fmac_f32_e32 v81, v46, v46
	v_fma_f32 v26, v27, v0, -v23
	v_fmac_f32_e32 v81, v26, v26
	v_fma_f32 v23, v28, v0, -v24
	v_fmac_f32_e32 v81, v23, v23
	v_fma_f32 v22, v29, v0, -v25
	v_fmac_f32_e32 v81, v22, v22
	s_waitcnt lgkmcnt(0)
	v_fma_f32 v32, v2, v0, -v82
	v_fma_f32 v31, v3, v0, -v83
	v_fma_f32 v29, v4, v0, -v84
	v_fma_f32 v27, v5, v0, -v85
	ds_read_b128 v[2:5], v80 offset:416
	v_fmac_f32_e32 v81, v78, v78
	v_fmac_f32_e32 v81, v77, v77
	v_fmac_f32_e32 v81, v76, v76
	v_fmac_f32_e32 v81, v33, v33
	v_fmac_f32_e32 v81, v32, v32
	s_waitcnt lgkmcnt(0)
	v_fma_f32 v30, v6, v0, -v2
	v_fma_f32 v28, v7, v0, -v3
	v_fma_f32 v25, v8, v0, -v4
	v_fma_f32 v24, v9, v0, -v5
	ds_read_b128 v[2:5], v80 offset:448
	v_fmac_f32_e32 v81, v31, v31
	v_fmac_f32_e32 v81, v29, v29
	v_fmac_f32_e32 v81, v27, v27
	v_fmac_f32_e32 v81, v30, v30
	v_fmac_f32_e32 v81, v28, v28
	s_waitcnt lgkmcnt(0)
	v_fma_f32 v21, v10, v0, -v2
	v_fma_f32 v19, v11, v0, -v3
	v_fma_f32 v18, v12, v0, -v4
	v_fma_f32 v13, v13, v0, -v5
	ds_read_b128 v[2:5], v80 offset:480
	v_fmac_f32_e32 v81, v25, v25
	v_fmac_f32_e32 v81, v24, v24
	v_fmac_f32_e32 v81, v21, v21
	v_fmac_f32_e32 v81, v19, v19
	v_fmac_f32_e32 v81, v18, v18
	s_waitcnt lgkmcnt(0)
	v_pk_fma_f32 v[8:9], v[14:15], v[0:1], v[2:3] op_sel_hi:[1,0,1] neg_lo:[0,0,1] neg_hi:[0,0,1]
	v_fmac_f32_e32 v81, v13, v13
	v_pk_mul_f32 v[2:3], v[8:9], v[8:9]
	v_pk_fma_f32 v[6:7], v[16:17], v[0:1], v[4:5] op_sel_hi:[1,0,1] neg_lo:[0,0,1] neg_hi:[0,0,1]
	v_add_f32_e32 v2, v81, v2
	v_add_f32_e32 v10, v2, v3
	v_pk_mul_f32 v[2:3], v[6:7], v[6:7]
	s_nop 0
	v_add_f32_e32 v0, v10, v2
	v_add_f32_e32 v0, v0, v3
	ds_bpermute_b32 v2, v208, v0
	s_waitcnt lgkmcnt(0)
; __device__ __forceinline__ unsigned cvt_pk_bf16(float lo, float hi) { unsigned r; asm volatile("v_cvt_pk_bf16_f32 %0, %1, %2" : "=v"(r) : "v"(lo), "v"(hi)); return r; }
; __device__ __forceinline__ void attn_unit(const bf16* Hb, const bf16* KD, const bf16* VD, bf16* MIX, int row0, int S, int head, int qb, float lam, const float* dng, float kn0, float kn1, LAS unsigned char* lds, int wave_u) {
;     ...
;         ss += __shfl_xor(ss, 32);
;         const float rn = (1.f - LAM_INIT) / sqrtf(ss * (1.f / 128.f) + 1e-5f);
;         bf16* orow = MIX + (size_t)(row0 + q0 + r32e) * D + head * 128;
; #pragma unroll
;         for (int b = 0; b < 4; ++b)
; #pragma unroll
;             for (int rg = 0; rg < 4; ++rg) { const int d = 32 * b + 8 * rg + 4 * hhe; const f32x4 g4 = *(const f32x4*)(dng + d);
;                 u32x2 w; w.x = cvt_pk_bf16(o[b][4 * rg + 0] * rn * g4.x, o[b][4 * rg + 1] * rn * g4.y); w.y = cvt_pk_bf16(o[b][4 * rg + 2] * rn * g4.z, o[b][4 * rg + 3] * rn * g4.w);
;                 *(u32x2*)(orow + d) = w; }
	v_add_f32_e32 v0, v0, v2
	v_fmamk_f32 v0, v0, 0x3c000000, v203
	v_cmp_gt_f32_e32 vcc, s50, v0
	v_mul_f32_e32 v2, 0x4f800000, v0
	s_nop 0
	v_cndmask_b32_e32 v0, v0, v2, vcc
	v_sqrt_f32_e32 v2, v0
	s_nop 0
	v_add_u32_e32 v3, -1, v2
	v_fma_f32 v4, -v3, v2, v0
	v_cmp_ge_f32_e64 s[0:1], 0, v4
	v_add_u32_e32 v4, 1, v2
	s_nop 0
	v_cndmask_b32_e64 v3, v2, v3, s[0:1]
	v_fma_f32 v2, -v4, v2, v0
	v_cmp_lt_f32_e64 s[0:1], 0, v2
	s_nop 1
	v_cndmask_b32_e64 v2, v3, v4, s[0:1]
	v_mul_f32_e32 v3, 0x37800000, v2
	v_cndmask_b32_e32 v2, v2, v3, vcc
	v_cmp_class_f32_e32 vcc, v0, v201
	s_nop 1
	v_cndmask_b32_e32 v0, v2, v0, vcc
	v_div_scale_f32 v2, s[0:1], v0, v0, s61
	v_rcp_f32_e32 v3, v2
	v_readlane_b32 s0, v253, 21
	v_readlane_b32 s1, v253, 22
	v_fma_f32 v4, -v2, v3, 1.0
	v_fmac_f32_e32 v3, v4, v3
	v_div_scale_f32 v4, vcc, s61, v0, s61
	v_mul_f32_e32 v5, v4, v3
	v_fma_f32 v10, -v2, v5, v4
	v_fmac_f32_e32 v5, v10, v3
	v_fma_f32 v2, -v2, v5, v4
	v_div_fmas_f32 v2, v2, v3, v5
	v_div_fixup_f32 v12, v2, v0, s61
	v_add_lshl_u32 v0, v79, s68, 11
	v_readlane_b32 s68, v251, 54
	v_lshl_add_u64 v[2:3], s[0:1], 0, v[0:1]
	v_readlane_b32 s69, v251, 55
	v_lshl_add_u64 v[10:11], v[2:3], 0, s[4:5]
	v_mul_f32_e32 v0, v68, v12
	v_readlane_b32 s70, v251, 56
	v_readlane_b32 s71, v251, 57
	v_readlane_b32 s72, v251, 58
	global_load_dwordx4 v[120:123], v66, s[68:69]
	global_load_dwordx4 v[124:127], v66, s[68:69] offset:32
	global_load_dwordx4 v[128:131], v66, s[68:69] offset:64
	global_load_dwordx4 v[132:135], v66, s[68:69] offset:96
	global_load_dwordx4 v[136:139], v66, s[68:69] offset:128
	global_load_dwordx4 v[140:143], v66, s[68:69] offset:160
	global_load_dwordx4 v[144:147], v66, s[68:69] offset:192
	global_load_dwordx4 v[148:151], v66, s[68:69] offset:224
	global_load_dwordx4 v[152:155], v66, s[68:69] offset:256
	global_load_dwordx4 v[156:159], v66, s[68:69] offset:288
	global_load_dwordx4 v[160:163], v66, s[68:69] offset:320
	global_load_dwordx4 v[164:167], v66, s[68:69] offset:352
	global_load_dwordx4 v[168:171], v66, s[68:69] offset:384
	global_load_dwordx4 v[172:175], v66, s[68:69] offset:416
	global_load_dwordx4 v[176:179], v66, s[68:69] offset:448
	global_load_dwordx4 v[180:183], v66, s[68:69] offset:480
	v_readlane_b32 s73, v251, 59
	v_readlane_b32 s74, v251, 60
	v_readlane_b32 s75, v251, 61
	v_readlane_b32 s76, v251, 62
	v_readlane_b32 s77, v251, 63
	v_readlane_b32 s78, v252, 0
	v_readlane_b32 s79, v252, 1
	v_readlane_b32 s80, v252, 2
	v_readlane_b32 s81, v252, 3
	v_readlane_b32 s82, v252, 4
	v_readlane_b32 s83, v252, 5
	s_waitcnt vmcnt(15)
	v_mul_f32_e32 v0, v120, v0
	v_mul_f32_e32 v2, v50, v12
	v_mul_f32_e32 v2, v121, v2
	v_cvt_pk_bf16_f32 v184, v0, v2
	v_mul_f32_e32 v0, v51, v12
	v_mul_f32_e32 v0, v122, v0
	v_mul_f32_e32 v2, v53, v12
	v_mul_f32_e32 v2, v123, v2
	v_cvt_pk_bf16_f32 v185, v0, v2
	v_lshlrev_b32_e32 v0, 3, v67
	v_lshl_add_u64 v[2:3], v[10:11], 0, v[0:1]
	v_mbcnt_lo_u32_b32 v194, -1, 0
	v_mbcnt_hi_u32_b32 v194, -1, v194
	v_and_b32_e32 v194, 32, v194
	v_lshrrev_b32_e32 v194, 2, v194
	v_mov_b32_e32 v195, 0
	v_lshl_add_u64 v[192:193], v[2:3], 0, v[194:195]
	v_mul_f32_e32 v0, v69, v12
	v_mul_f32_e32 v4, v55, v12
	v_mul_f32_e32 v5, v57, v12
	s_waitcnt vmcnt(14)
	v_mul_f32_e32 v0, v124, v0
	v_mul_f32_e32 v4, v125, v4
	v_cvt_pk_bf16_f32 v186, v0, v4
	v_mul_f32_e32 v0, v56, v12
	v_mul_f32_e32 v5, v127, v5
	v_mul_f32_e32 v0, v126, v0
	v_cvt_pk_bf16_f32 v187, v0, v5
	s_nop 1
	v_permlane32_swap_b32_e32 v184, v186
	v_permlane32_swap_b32_e32 v185, v187
	global_store_dwordx4 v[192:193], v[184:187], off
	v_mul_f32_e32 v0, v70, v12
	v_mul_f32_e32 v4, v58, v12
	v_mul_f32_e32 v5, v52, v12
	s_waitcnt vmcnt(14)
	v_mul_f32_e32 v0, v0, v128
	v_mul_f32_e32 v4, v4, v129
	v_cvt_pk_bf16_f32 v188, v0, v4
	v_mul_f32_e32 v0, v54, v12
	v_mul_f32_e32 v5, v5, v131
	v_mul_f32_e32 v0, v0, v130
	v_cvt_pk_bf16_f32 v189, v0, v5
	v_mul_f32_e32 v0, v71, v12
	v_mul_f32_e32 v4, v63, v12
	v_mul_f32_e32 v5, v61, v12
	s_waitcnt vmcnt(13)
	v_mul_f32_e32 v0, v0, v132
	v_mul_f32_e32 v4, v4, v133
	v_cvt_pk_bf16_f32 v190, v0, v4
	v_mul_f32_e32 v0, v62, v12
	v_mul_f32_e32 v5, v5, v135
	v_mul_f32_e32 v0, v0, v134
	v_cvt_pk_bf16_f32 v191, v0, v5
	s_nop 1
	v_permlane32_swap_b32_e32 v188, v190
	v_permlane32_swap_b32_e32 v189, v191
	global_store_dwordx4 v[192:193], v[188:191], off offset:32
	v_mul_f32_e32 v0, v60, v12
	v_mul_f32_e32 v4, v59, v12
	v_mul_f32_e32 v5, v34, v12
	s_waitcnt vmcnt(13)
; __device__ __forceinline__ unsigned cvt_pk_bf16(float lo, float hi) { unsigned r; asm volatile("v_cvt_pk_bf16_f32 %0, %1, %2" : "=v"(r) : "v"(lo), "v"(hi)); return r; }
; __device__ __forceinline__ void attn_unit(const bf16* Hb, const bf16* KD, const bf16* VD, bf16* MIX, int row0, int S, int head, int qb, float lam, const float* dng, float kn0, float kn1, LAS unsigned char* lds, int wave_u) {
;     ...
;         bf16* orow = MIX + (size_t)(row0 + q0 + r32e) * D + head * 128;
; #pragma unroll
;         for (int b = 0; b < 4; ++b)
; #pragma unroll
;             for (int rg = 0; rg < 4; ++rg) { const int d = 32 * b + 8 * rg + 4 * hhe; const f32x4 g4 = *(const f32x4*)(dng + d);
;                 u32x2 w; w.x = cvt_pk_bf16(o[b][4 * rg + 0] * rn * g4.x, o[b][4 * rg + 1] * rn * g4.y); w.y = cvt_pk_bf16(o[b][4 * rg + 2] * rn * g4.z, o[b][4 * rg + 3] * rn * g4.w);
;                 *(u32x2*)(orow + d) = w; }
	v_mul_f32_e32 v0, v0, v136
	v_mul_f32_e32 v4, v4, v137
	v_cvt_pk_bf16_f32 v184, v0, v4
	v_mul_f32_e32 v0, v35, v12
	v_mul_f32_e32 v5, v5, v139
	v_mul_f32_e32 v0, v0, v138
	v_cvt_pk_bf16_f32 v185, v0, v5
	v_mul_f32_e32 v0, v72, v12
	v_mul_f32_e32 v4, v65, v12
	v_mul_f32_e32 v5, v41, v12
	s_waitcnt vmcnt(12)
	v_mul_f32_e32 v0, v0, v140
	v_mul_f32_e32 v4, v4, v141
	v_cvt_pk_bf16_f32 v186, v0, v4
	v_mul_f32_e32 v0, v64, v12
	v_mul_f32_e32 v5, v5, v143
	v_mul_f32_e32 v0, v0, v142
	v_cvt_pk_bf16_f32 v187, v0, v5
	s_nop 1
	v_permlane32_swap_b32_e32 v184, v186
	v_permlane32_swap_b32_e32 v185, v187
	global_store_dwordx4 v[192:193], v[184:187], off offset:64
	v_mul_f32_e32 v0, v39, v12
	v_mul_f32_e32 v4, v38, v12
	v_mul_f32_e32 v5, v36, v12
	s_waitcnt vmcnt(12)
	v_mul_f32_e32 v0, v0, v144
	v_mul_f32_e32 v4, v4, v145
	v_cvt_pk_bf16_f32 v188, v0, v4
	v_mul_f32_e32 v0, v37, v12
	v_mul_f32_e32 v5, v5, v147
	v_mul_f32_e32 v0, v0, v146
	v_cvt_pk_bf16_f32 v189, v0, v5
	v_mul_f32_e32 v0, v73, v12
	v_mul_f32_e32 v4, v47, v12
	v_mul_f32_e32 v5, v44, v12
	s_waitcnt vmcnt(11)
	v_mul_f32_e32 v0, v0, v148
	v_mul_f32_e32 v4, v4, v149
	v_cvt_pk_bf16_f32 v190, v0, v4
	v_mul_f32_e32 v0, v45, v12
	v_mul_f32_e32 v5, v5, v151
	v_mul_f32_e32 v0, v0, v150
	v_cvt_pk_bf16_f32 v191, v0, v5
	s_nop 1
	v_permlane32_swap_b32_e32 v188, v190
	v_permlane32_swap_b32_e32 v189, v191
	global_store_dwordx4 v[192:193], v[188:191], off offset:96
	v_mul_f32_e32 v0, v43, v12
	v_mul_f32_e32 v4, v42, v12
	v_mul_f32_e32 v5, v20, v12
	s_waitcnt vmcnt(11)
	v_mul_f32_e32 v0, v0, v152
	v_mul_f32_e32 v4, v4, v153
	v_cvt_pk_bf16_f32 v184, v0, v4
	v_mul_f32_e32 v0, v40, v12
	v_mul_f32_e32 v5, v5, v155
	v_mul_f32_e32 v0, v0, v154
	v_cvt_pk_bf16_f32 v185, v0, v5
	v_mul_f32_e32 v0, v75, v12
	v_mul_f32_e32 v4, v74, v12
	v_mul_f32_e32 v5, v48, v12
	s_waitcnt vmcnt(10)
	v_mul_f32_e32 v0, v0, v156
	v_mul_f32_e32 v4, v4, v157
	v_cvt_pk_bf16_f32 v186, v0, v4
	v_mul_f32_e32 v0, v49, v12
	v_mul_f32_e32 v5, v5, v159
	v_mul_f32_e32 v0, v0, v158
	v_cvt_pk_bf16_f32 v187, v0, v5
	s_nop 1
	v_permlane32_swap_b32_e32 v184, v186
	v_permlane32_swap_b32_e32 v185, v187
	global_store_dwordx4 v[192:193], v[184:187], off offset:128
	v_mul_f32_e32 v0, v46, v12
	v_mul_f32_e32 v4, v26, v12
	v_mul_f32_e32 v5, v22, v12
	s_waitcnt vmcnt(10)
	v_mul_f32_e32 v0, v0, v160
	v_mul_f32_e32 v4, v4, v161
	v_cvt_pk_bf16_f32 v188, v0, v4
	v_mul_f32_e32 v0, v23, v12
	v_mul_f32_e32 v5, v5, v163
	v_mul_f32_e32 v0, v0, v162
	v_cvt_pk_bf16_f32 v189, v0, v5
	v_mul_f32_e32 v0, v78, v12
	v_mul_f32_e32 v4, v77, v12
	v_mul_f32_e32 v5, v33, v12
	s_waitcnt vmcnt(9)
	v_mul_f32_e32 v0, v0, v164
	v_mul_f32_e32 v4, v4, v165
	v_cvt_pk_bf16_f32 v190, v0, v4
	v_mul_f32_e32 v0, v76, v12
	v_mul_f32_e32 v5, v5, v167
	v_mul_f32_e32 v0, v0, v166
	v_cvt_pk_bf16_f32 v191, v0, v5
	s_nop 1
	v_permlane32_swap_b32_e32 v188, v190
	v_permlane32_swap_b32_e32 v189, v191
	global_store_dwordx4 v[192:193], v[188:191], off offset:160
	v_mul_f32_e32 v0, v32, v12
	v_mul_f32_e32 v4, v31, v12
	v_mul_f32_e32 v5, v27, v12
	s_waitcnt vmcnt(9)
	v_mul_f32_e32 v0, v0, v168
	v_mul_f32_e32 v4, v4, v169
	v_cvt_pk_bf16_f32 v184, v0, v4
	v_mul_f32_e32 v0, v29, v12
	v_mul_f32_e32 v5, v5, v171
	v_mul_f32_e32 v0, v0, v170
	v_cvt_pk_bf16_f32 v185, v0, v5
	v_mul_f32_e32 v0, v30, v12
	v_mul_f32_e32 v4, v28, v12
	v_mul_f32_e32 v5, v24, v12
	s_waitcnt vmcnt(8)
	v_mul_f32_e32 v0, v0, v172
	v_mul_f32_e32 v4, v4, v173
	v_cvt_pk_bf16_f32 v186, v0, v4
	v_mul_f32_e32 v0, v25, v12
	v_mul_f32_e32 v5, v5, v175
	v_mul_f32_e32 v0, v0, v174
	v_cvt_pk_bf16_f32 v187, v0, v5
	s_nop 1
	v_permlane32_swap_b32_e32 v184, v186
	v_permlane32_swap_b32_e32 v185, v187
	global_store_dwordx4 v[192:193], v[184:187], off offset:192
	v_mul_f32_e32 v0, v21, v12
	v_mul_f32_e32 v4, v19, v12
	v_mul_f32_e32 v5, v13, v12
	s_waitcnt vmcnt(8)
	v_mul_f32_e32 v0, v0, v176
	v_mul_f32_e32 v4, v4, v177
	v_cvt_pk_bf16_f32 v188, v0, v4
	v_mul_f32_e32 v0, v18, v12
	v_mul_f32_e32 v5, v5, v179
	v_mul_f32_e32 v0, v0, v178
	v_cvt_pk_bf16_f32 v189, v0, v5
	v_mul_f32_e32 v0, v8, v12
	v_mul_f32_e32 v4, v9, v12
	v_mul_f32_e32 v5, v7, v12
	s_waitcnt vmcnt(7)
	v_mul_f32_e32 v0, v0, v180
	v_mul_f32_e32 v4, v4, v181
	v_cvt_pk_bf16_f32 v190, v0, v4
	v_mul_f32_e32 v0, v6, v12
	v_mul_f32_e32 v5, v5, v183
	v_mul_f32_e32 v0, v0, v182
	v_cvt_pk_bf16_f32 v191, v0, v5
	s_nop 1
	v_permlane32_swap_b32_e32 v188, v190
	v_permlane32_swap_b32_e32 v189, v191
	global_store_dwordx4 v[192:193], v[188:191], off offset:224
	s_branch .LBB0_607
